# lat-A loop: the four K-fragment reads of each key sub-block issued together behind counted waits
# baseline (speedup 1.0000x reference)
.LBB0_228:
	v_lshl_or_b32 v204, s41, 14, v165
	v_lshl_add_u32 v13, v203, 1, v204
	v_lshl_add_u32 v14, v202, 1, v204
	v_lshl_add_u32 v15, v201, 1, v204
	v_lshl_add_u32 v12, v167, 1, v204
	ds_read_b128 v[4:7], v13
	ds_read_b128 v[8:11], v14
	ds_read_b128 v[238:241], v15
	ds_read_b128 v[242:245], v12
	v_cmp_lt_i32_e32 vcc, v180, v182
	s_nop 1
	v_cndmask_b32_e32 v0, v179, v180, vcc
	v_lshlrev_b32_e32 v0, 2, v0
	s_waitcnt lgkmcnt(3)
	v_mfma_f32_32x32x16_bf16 v[96:111], v[4:7], v[136:139], 0
	v_mfma_f32_32x32x16_bf16 v[80:95], v[4:7], v[140:143], 0
	s_waitcnt lgkmcnt(2)
	v_mfma_f32_32x32x16_bf16 v[96:111], v[8:11], v[124:127], v[96:111]
	v_mfma_f32_32x32x16_bf16 v[80:95], v[8:11], v[132:135], v[80:95]
	s_waitcnt lgkmcnt(1)
	v_mfma_f32_32x32x16_bf16 v[96:111], v[238:241], v[120:123], v[96:111]
	v_mfma_f32_32x32x16_bf16 v[80:95], v[238:241], v[128:131], v[80:95]
	s_waitcnt lgkmcnt(0)
	v_mfma_f32_32x32x16_bf16 v[96:111], v[242:245], v[112:115], v[96:111]
	v_mfma_f32_32x32x16_bf16 v[80:95], v[242:245], v[116:119], v[80:95]
	s_nop 10
	v_max_f32_e32 v4, v97, v97
	v_max_f32_e32 v5, v96, v96
	v_max_f32_e32 v4, v5, v4
	v_max3_f32 v4, v4, v98, v99
	v_max3_f32 v4, v4, v100, v101
	v_max3_f32 v4, v4, v102, v103
	v_max3_f32 v4, v4, v104, v105
	v_max3_f32 v4, v4, v106, v107
	v_max3_f32 v4, v4, v108, v109
	v_max3_f32 v4, v4, v110, v111
	v_mov_b32_e32 v5, v4
	s_nop 1
	v_permlane32_swap_b32_e32 v5, v4
	s_nop 1
	s_waitcnt lgkmcnt(0)
	v_max_f32_e32 v5, v5, v5
	v_max_f32_e32 v4, v4, v5
	v_add_f32_e32 v5, 0x41000000, v1
	v_cmp_gt_f32_e32 vcc, v4, v5
	s_cbranch_vccz .LBB0_230
	v_max_f32_e32 v4, v4, v4
	v_max_f32_e32 v5, v1, v1
	v_max_f32_e32 v5, v5, v4
	v_sub_f32_e32 v1, v1, v5
	v_exp_f32_e32 v4, v1
	v_mov_b32_e32 v1, v5
	v_mul_f32_e32 v3, v3, v4
	v_pk_mul_f32 v[78:79], v[78:79], v[4:5] op_sel_hi:[1,0]
	v_pk_mul_f32 v[76:77], v[76:77], v[4:5] op_sel_hi:[1,0]
	v_pk_mul_f32 v[74:75], v[74:75], v[4:5] op_sel_hi:[1,0]
	v_pk_mul_f32 v[72:73], v[72:73], v[4:5] op_sel_hi:[1,0]
	v_pk_mul_f32 v[70:71], v[70:71], v[4:5] op_sel_hi:[1,0]
	v_pk_mul_f32 v[68:69], v[68:69], v[4:5] op_sel_hi:[1,0]
	v_pk_mul_f32 v[66:67], v[66:67], v[4:5] op_sel_hi:[1,0]
	v_pk_mul_f32 v[64:65], v[64:65], v[4:5] op_sel_hi:[1,0]
	v_pk_mul_f32 v[62:63], v[62:63], v[4:5] op_sel_hi:[1,0]
	v_pk_mul_f32 v[60:61], v[60:61], v[4:5] op_sel_hi:[1,0]
	v_pk_mul_f32 v[58:59], v[58:59], v[4:5] op_sel_hi:[1,0]
	v_pk_mul_f32 v[56:57], v[56:57], v[4:5] op_sel_hi:[1,0]
	v_pk_mul_f32 v[54:55], v[54:55], v[4:5] op_sel_hi:[1,0]
	v_pk_mul_f32 v[52:53], v[52:53], v[4:5] op_sel_hi:[1,0]
	v_pk_mul_f32 v[50:51], v[50:51], v[4:5] op_sel_hi:[1,0]
	v_pk_mul_f32 v[48:49], v[48:49], v[4:5] op_sel_hi:[1,0]

.LBB0_232:
	v_sub_f32_e32 v4, v96, v1
	v_exp_f32_e32 v4, v4
	v_sub_f32_e32 v6, v97, v1
	v_exp_f32_e32 v6, v6
	v_sub_f32_e32 v7, v98, v1
	v_exp_f32_e32 v7, v7
	v_sub_f32_e32 v8, v99, v1
	v_exp_f32_e32 v8, v8
	v_add_f32_e32 v5, v6, v4
	v_add_f32_e32 v5, v7, v5
	v_add_f32_e32 v5, v8, v5
	v_cvt_pk_bf16_f32 v97, v7, v8
	v_sub_f32_e32 v8, v80, v159
	v_exp_f32_e32 v207, v8
	v_sub_f32_e32 v8, v81, v159
	v_exp_f32_e32 v209, v8
	v_sub_f32_e32 v8, v82, v159
	v_exp_f32_e32 v210, v8
	v_sub_f32_e32 v8, v83, v159
	v_exp_f32_e32 v211, v8
	v_sub_f32_e32 v8, v84, v159
	v_exp_f32_e32 v212, v8
	v_sub_f32_e32 v8, v85, v159
	v_exp_f32_e32 v213, v8
	v_sub_f32_e32 v8, v86, v159
	v_exp_f32_e32 v214, v8
	v_sub_f32_e32 v8, v87, v159
	v_exp_f32_e32 v215, v8
	v_sub_f32_e32 v8, v88, v159
	v_exp_f32_e32 v216, v8
	v_sub_f32_e32 v8, v89, v159
	v_lshl_add_u32 v204, v154, 1, v204
	v_exp_f32_e32 v217, v8
	v_sub_f32_e32 v8, v90, v159
	v_lshl_add_u32 v84, v164, 1, v204
	v_lshl_add_u32 v88, v163, 1, v204
	v_exp_f32_e32 v218, v8
	v_sub_f32_e32 v8, v91, v159
	ds_read_b64 v[222:223], v84 offset:8192
	ds_read_b64 v[226:227], v84 offset:12288
	ds_read_b64 v[224:225], v88 offset:8192
	ds_read_b64 v[228:229], v88 offset:12288
	v_exp_f32_e32 v219, v8
	v_sub_f32_e32 v8, v92, v159
	v_sub_f32_e32 v9, v100, v1
	v_sub_f32_e32 v96, v103, v1
	v_exp_f32_e32 v220, v8
	v_sub_f32_e32 v8, v93, v159
	v_exp_f32_e32 v9, v9
	v_sub_f32_e32 v10, v101, v1
	v_exp_f32_e32 v99, v96
	v_sub_f32_e32 v96, v104, v1
	v_exp_f32_e32 v205, v8
	v_sub_f32_e32 v8, v94, v159
	v_exp_f32_e32 v10, v10
	v_sub_f32_e32 v11, v102, v1
	v_exp_f32_e32 v100, v96
	v_sub_f32_e32 v96, v105, v1
	v_exp_f32_e32 v206, v8
	v_sub_f32_e32 v8, v95, v159
	s_waitcnt lgkmcnt(0)
	v_exp_f32_e32 v11, v11
	v_exp_f32_e32 v101, v96
	v_sub_f32_e32 v96, v106, v1
	v_exp_f32_e32 v102, v96
	v_sub_f32_e32 v96, v107, v1
	v_add_f32_e32 v5, v9, v5
	v_exp_f32_e32 v103, v96
	v_sub_f32_e32 v96, v108, v1
	v_add_f32_e32 v5, v10, v5
	v_exp_f32_e32 v104, v96
	v_sub_f32_e32 v96, v109, v1
	v_cvt_pk_bf16_f32 v80, v207, v209
	v_cvt_pk_bf16_f32 v81, v210, v211
	v_cvt_pk_bf16_f32 v82, v212, v213
	v_cvt_pk_bf16_f32 v83, v214, v215
	v_add_f32_e32 v5, v11, v5
	v_exp_f32_e32 v105, v96
	v_sub_f32_e32 v96, v110, v1
	v_mfma_f32_32x32x16_bf16 v[32:47], v[222:225], v[80:83], v[32:47]
	v_lshl_add_u32 v84, v160, 1, v204
	v_add_f32_e32 v5, v99, v5
	v_exp_f32_e32 v106, v96
	v_sub_f32_e32 v96, v111, v1
	ds_read_b64 v[232:233], v84 offset:8192
	ds_read_b64 v[236:237], v84 offset:12288
	v_add_f32_e32 v5, v100, v5
	v_exp_f32_e32 v107, v96
	v_mfma_f32_32x32x16_bf16 v[16:31], v[226:229], v[80:83], v[16:31]
	v_lshl_add_u32 v80, v161, 1, v204
	ds_read_b64 v[230:231], v80 offset:8192
	ds_read_b64 v[234:235], v80 offset:12288
	v_cvt_pk_bf16_f32 v96, v4, v6
	v_cvt_pk_bf16_f32 v98, v9, v10
	v_cvt_pk_bf16_f32 v99, v11, v99
	v_add_f32_e32 v5, v101, v5
	v_add_f32_e32 v5, v102, v5
	v_mfma_f32_32x32x16_bf16 v[64:79], v[222:225], v[96:99], v[64:79]
	v_add_f32_e32 v5, v103, v5
	v_add_f32_e32 v5, v104, v5
	v_add_f32_e32 v5, v105, v5
	v_add_f32_e32 v5, v106, v5
	v_add_f32_e32 v5, v107, v5
	v_add_f32_e32 v3, v3, v5
	v_cvt_pk_bf16_f32 v4, v100, v101
	v_mfma_f32_32x32x16_bf16 v[48:63], v[226:229], v[96:99], v[48:63]
	s_waitcnt lgkmcnt(0)
	v_cvt_pk_bf16_f32 v5, v102, v103
	v_cvt_pk_bf16_f32 v6, v104, v105
	v_cvt_pk_bf16_f32 v7, v106, v107
	v_exp_f32_e32 v208, v8
	v_cvt_pk_bf16_f32 v8, v216, v217
	v_mfma_f32_32x32x16_bf16 v[64:79], v[230:233], v[4:7], v[64:79]
	v_cvt_pk_bf16_f32 v9, v218, v219
	v_cvt_pk_bf16_f32 v10, v220, v205
	v_cvt_pk_bf16_f32 v11, v206, v208
	v_mfma_f32_32x32x16_bf16 v[48:63], v[234:237], v[4:7], v[48:63]
	ds_read_b128 v[4:7], v13 offset:4096
	ds_read_b128 v[238:241], v14 offset:4096
	ds_read_b128 v[242:245], v15 offset:4096
	ds_read_b128 v[246:249], v12 offset:4096
	v_mfma_f32_32x32x16_bf16 v[32:47], v[230:233], v[8:11], v[32:47]
	v_mfma_f32_32x32x16_bf16 v[16:31], v[234:237], v[8:11], v[16:31]
	s_waitcnt lgkmcnt(3)
	v_mfma_f32_32x32x16_bf16 v[96:111], v[4:7], v[136:139], 0
	v_mfma_f32_32x32x16_bf16 v[80:95], v[4:7], v[140:143], 0
	s_waitcnt lgkmcnt(2)
	v_mfma_f32_32x32x16_bf16 v[96:111], v[238:241], v[124:127], v[96:111]
	v_mfma_f32_32x32x16_bf16 v[80:95], v[238:241], v[132:135], v[80:95]
	s_waitcnt lgkmcnt(1)
	v_mfma_f32_32x32x16_bf16 v[96:111], v[242:245], v[120:123], v[96:111]
	v_mfma_f32_32x32x16_bf16 v[80:95], v[242:245], v[128:131], v[80:95]
	s_waitcnt lgkmcnt(0)
	v_mfma_f32_32x32x16_bf16 v[96:111], v[246:249], v[112:115], v[96:111]
	v_mfma_f32_32x32x16_bf16 v[80:95], v[246:249], v[116:119], v[80:95]
	s_nop 10
	v_max_f32_e32 v4, v97, v97
	v_max_f32_e32 v5, v96, v96
	v_max_f32_e32 v4, v5, v4
	v_max3_f32 v4, v4, v98, v99
	v_max3_f32 v4, v4, v100, v101
	v_max3_f32 v4, v4, v102, v103
	v_max3_f32 v4, v4, v104, v105
	v_max3_f32 v4, v4, v106, v107
	v_max3_f32 v4, v4, v108, v109
	v_max3_f32 v4, v4, v110, v111
	v_mov_b32_e32 v5, v4
	s_nop 1
	v_permlane32_swap_b32_e32 v5, v4
	s_nop 1
	s_waitcnt lgkmcnt(0)
	v_max_f32_e32 v5, v5, v5
	v_max_f32_e32 v4, v4, v5
	v_add_f32_e32 v5, 0x41000000, v1
	v_cmp_gt_f32_e32 vcc, v4, v5
	s_cbranch_vccz .LBB0_234
	v_max_f32_e32 v4, v4, v4
	v_max_f32_e32 v5, v1, v1
	v_max_f32_e32 v5, v5, v4
	v_sub_f32_e32 v1, v1, v5
	v_exp_f32_e32 v4, v1
	v_mov_b32_e32 v1, v5
	v_mul_f32_e32 v3, v3, v4
	v_pk_mul_f32 v[78:79], v[78:79], v[4:5] op_sel_hi:[1,0]
	v_pk_mul_f32 v[76:77], v[76:77], v[4:5] op_sel_hi:[1,0]
	v_pk_mul_f32 v[74:75], v[74:75], v[4:5] op_sel_hi:[1,0]
	v_pk_mul_f32 v[72:73], v[72:73], v[4:5] op_sel_hi:[1,0]
	v_pk_mul_f32 v[70:71], v[70:71], v[4:5] op_sel_hi:[1,0]
	v_pk_mul_f32 v[68:69], v[68:69], v[4:5] op_sel_hi:[1,0]
	v_pk_mul_f32 v[66:67], v[66:67], v[4:5] op_sel_hi:[1,0]
	v_pk_mul_f32 v[64:65], v[64:65], v[4:5] op_sel_hi:[1,0]
	v_pk_mul_f32 v[62:63], v[62:63], v[4:5] op_sel_hi:[1,0]
	v_pk_mul_f32 v[60:61], v[60:61], v[4:5] op_sel_hi:[1,0]
	v_pk_mul_f32 v[58:59], v[58:59], v[4:5] op_sel_hi:[1,0]
	v_pk_mul_f32 v[56:57], v[56:57], v[4:5] op_sel_hi:[1,0]
	v_pk_mul_f32 v[54:55], v[54:55], v[4:5] op_sel_hi:[1,0]
	v_pk_mul_f32 v[52:53], v[52:53], v[4:5] op_sel_hi:[1,0]
	v_pk_mul_f32 v[50:51], v[50:51], v[4:5] op_sel_hi:[1,0]
	v_pk_mul_f32 v[48:49], v[48:49], v[4:5] op_sel_hi:[1,0]
